# FO1 on MM1+PL1+PW1 R0=32768: the two fill passes of the weight-product unit have their loads in flight together (second pass on registers +100)
# speedup vs baseline: 1.0039x; 1.0039x over previous
; #define LAS __attribute__((address_space(3)))
; __device__ void p_weights_prod(const Args& a, LAS unsigned char* lds) {
;     ...
;     for (int u = blockIdx.x; u < 256; u += gridDim.x) {
;         const int l = u >> 7, g = (u >> 5) & 3, kblk = u & 31, pn = 7 + g;
;         __syncthreads();
;         {
;             const int rr = tid >> 4, c8 = (tid & 15) * 8;
;             const float* src = a.w_in + (size_t)l * DM * INW + (size_t)(kblk * 32 + rr) * INW + 1280 + g * 128 + c8;
;             const f32x4* msrc = (const f32x4*)(MM + (size_t)(l * 4 + g) * 128 * 256) + tid;
;             f32x4 mreg[16];
; #pragma unroll
;             for (int j = 0; j < 16; ++j) mreg[j] = msrc[j * NTHREADS];
;             *(LAS f32x4*)(wt + rr * 128 + c8) = *(const f32x4*)src; *(LAS f32x4*)(wt + rr * 128 + c8 + 4) = *(const f32x4*)(src + 4);
; #pragma unroll
;             for (int j = 0; j < 16; ++j) ((LAS f32x4*)mmt)[tid + j * NTHREADS] = mreg[j];
;         }
.LBB0_86:
.LBB0_87:
	v_readfirstlane_b32 s100, v0
	s_nop 3
	s_cmp_ge_u32 s100, 0x100
	s_cbranch_scc1 .Lpw_x
	v_mov_b32_e32 v8, v0
	v_lshlrev_b32_e32 v10, 4, v8
	s_load_dword s9, s[0:1], 0x60
	s_add_u32 s6, s40, 0x1fb00000
	v_lshlrev_b32_e32 v1, 1, v8
	v_and_b32_e32 v2, 0x90, v10
	s_movk_i32 s3, 0x6c
	v_lshlrev_b32_e32 v3, 3, v8
	v_ashrrev_i32_e32 v9, 31, v8
	s_addc_u32 s7, s41, 0
	v_and_or_b32 v2, v1, s3, v2
	v_ashrrev_i32_e32 v11, 6, v8
	v_ashrrev_i32_e32 v1, 4, v8
	v_and_b32_e32 v4, 0x78, v3
	v_lshl_add_u64 v[6:7], v[8:9], 4, s[40:41]
	s_mov_b64 s[4:5], 0x20a00000
	v_and_b32_e32 v8, 63, v8
	v_lshl_add_u64 v[6:7], v[6:7], 0, s[4:5]
	v_lshlrev_b32_e32 v3, 9, v1
	v_lshlrev_b32_e32 v9, 2, v4
	v_add_u32_e32 v24, 0, v10
	s_add_u32 s4, s0, 0x60
	v_lshl_add_u32 v8, v8, 4, 0
	v_mov_b32_e32 v5, 0
	s_mov_b32 s11, 0
	v_add3_u32 v3, 0, v3, v9
	s_movk_i32 s3, 0x4000
	v_add_u32_e32 v25, 0x4000, v24
	v_lshl_add_u32 v26, v11, 11, 0
	v_lshlrev_b32_e32 v27, 2, v11
	s_addc_u32 s5, s1, 0
	s_mov_b32 s14, 0x14000
	v_add_u32_e32 v28, 0x14000, v24
	s_mov_b32 s15, 0x16000
	v_add_u32_e32 v29, 0x16000, v24
	s_mov_b32 s33, 0x18000
	v_add_u32_e32 v30, 0x18000, v24
	s_mov_b32 s34, 0x1a000
	v_add_u32_e32 v31, 0x1a000, v24
	s_mov_b32 s35, 0x1c000
	v_add_u32_e32 v32, 0x1c000, v24
	s_mov_b32 s36, 0x1e000
	v_add_u32_e32 v33, 0x1e000, v24
	v_add_u32_e32 v34, 0x20000, v24
	v_add_u32_e32 v35, 0x22000, v24
	v_add_u32_e32 v36, 0x4000, v8
	s_movk_i32 s37, 0x2400
	s_movk_i32 s44, 0x2000
	s_movk_i32 s45, 0x6000
	s_mov_b32 s46, 0x8000
	s_mov_b32 s47, 0xa000
	s_mov_b32 s48, 0xc000
	s_mov_b32 s49, 0xe000
	s_mov_b32 s50, 0x10000
	s_mov_b32 s51, 0x12000
	v_lshlrev_b32_e32 v4, 2, v4
	s_mov_b64 s[12:13], 0x1400
	s_movk_i32 s52, 0x1000
	s_mov_b32 s53, s2
	s_ashr_i32 s55, s53, 7
	s_bfe_u32 s54, s53, 0x20005
	s_mul_i32 s56, s55, 0x900000
	s_mul_hi_i32 s10, s55, 0x900000
	s_add_u32 s58, s22, s56
	s_addc_u32 s59, s23, s10
	s_lshl_b32 s10, s53, 5
	s_and_b32 s56, s10, 0x3e0
	v_add_u32_e32 v10, s56, v1
	v_mov_b64_e32 v[8:9], s[58:59]
	v_mad_i64_i32 v[8:9], s[58:59], v10, s37, v[8:9]
	s_lshl_b32 s10, s54, 9
	v_lshl_add_u64 v[8:9], v[8:9], 0, s[10:11]
	s_lshl_b32 s10, s55, 2
	s_or_b32 s58, s10, s54
	v_lshl_add_u64 v[8:9], v[8:9], 0, v[4:5]
	s_ashr_i32 s59, s58, 31
	v_add_co_u32_e32 v10, vcc, s52, v8
	s_lshl_b64 s[58:59], s[58:59], 17
	s_nop 0
	v_addc_co_u32_e32 v11, vcc, 0, v9, vcc
	v_lshl_add_u64 v[86:87], v[6:7], 0, s[58:59]
	v_add_co_u32_e32 v20, vcc, s44, v86
	v_lshl_add_u64 v[12:13], v[8:9], 0, s[12:13]
	s_nop 0
	v_addc_co_u32_e32 v21, vcc, 0, v87, vcc
	v_add_co_u32_e32 v38, vcc, s3, v86
	s_waitcnt lgkmcnt(0)
	s_nop 0
	v_addc_co_u32_e32 v39, vcc, 0, v87, vcc
	v_add_co_u32_e32 v42, vcc, s45, v86
	s_barrier
	s_nop 0
	v_addc_co_u32_e32 v43, vcc, 0, v87, vcc
	v_add_co_u32_e32 v46, vcc, s46, v86
	s_nop 1
	v_addc_co_u32_e32 v47, vcc, 0, v87, vcc
	v_add_co_u32_e32 v50, vcc, s47, v86
	global_load_dwordx4 v[8:11], v[10:11], off offset:1024
	s_nop 0
	global_load_dwordx4 v[12:15], v[12:13], off offset:16
	v_addc_co_u32_e32 v51, vcc, 0, v87, vcc
	v_add_co_u32_e32 v54, vcc, s48, v86
	global_load_dwordx4 v[16:19], v[86:87], off
	s_nop 0
	global_load_dwordx4 v[20:23], v[20:21], off
	v_addc_co_u32_e32 v55, vcc, 0, v87, vcc
	v_add_co_u32_e32 v58, vcc, s49, v86
	global_load_dwordx4 v[38:41], v[38:39], off
	s_nop 0
	global_load_dwordx4 v[42:45], v[42:43], off
	v_addc_co_u32_e32 v59, vcc, 0, v87, vcc
	v_add_co_u32_e32 v62, vcc, s50, v86
	global_load_dwordx4 v[46:49], v[46:47], off
	s_nop 0
	global_load_dwordx4 v[50:53], v[50:51], off
	v_addc_co_u32_e32 v63, vcc, 0, v87, vcc
	v_add_co_u32_e32 v66, vcc, s51, v86
	s_mov_b32 s10, -4
	s_nop 0
	v_addc_co_u32_e32 v67, vcc, 0, v87, vcc
	v_add_co_u32_e32 v70, vcc, s14, v86
	v_mov_b32_e32 v37, v26
	s_nop 0
	v_addc_co_u32_e32 v71, vcc, 0, v87, vcc
	v_add_co_u32_e32 v74, vcc, s15, v86
	s_nop 1
	v_addc_co_u32_e32 v75, vcc, 0, v87, vcc
	v_add_co_u32_e32 v78, vcc, s33, v86
	global_load_dwordx4 v[54:57], v[54:55], off
	s_nop 0
	global_load_dwordx4 v[58:61], v[58:59], off
	s_nop 0
	global_load_dwordx4 v[62:65], v[62:63], off
	s_nop 0
	global_load_dwordx4 v[66:69], v[66:67], off
	s_nop 0
	global_load_dwordx4 v[70:73], v[70:71], off
	s_nop 0
	global_load_dwordx4 v[74:77], v[74:75], off
	v_addc_co_u32_e32 v79, vcc, 0, v87, vcc
	v_add_co_u32_e32 v82, vcc, s34, v86
	s_nop 1
	v_addc_co_u32_e32 v83, vcc, 0, v87, vcc
	v_add_co_u32_e32 v88, vcc, s35, v86
	global_load_dwordx4 v[78:81], v[78:79], off
	s_nop 0
	global_load_dwordx4 v[82:85], v[82:83], off
	v_addc_co_u32_e32 v89, vcc, 0, v87, vcc
	v_add_co_u32_e32 v90, vcc, s36, v86
	s_nop 1
	v_addc_co_u32_e32 v91, vcc, 0, v87, vcc
	global_load_dwordx4 v[86:89], v[88:89], off
	s_nop 0
	global_load_dwordx4 v[90:93], v[90:91], off
	v_add_u32_e32 v108, 0x100, v0
	v_lshlrev_b32_e32 v110, 4, v108
	s_load_dword s9, s[0:1], 0x60
	s_add_u32 s6, s40, 0x1fb00000
	v_lshlrev_b32_e32 v101, 1, v108
	v_and_b32_e32 v102, 0x90, v110
	s_movk_i32 s3, 0x6c
	v_lshlrev_b32_e32 v103, 3, v108
	v_ashrrev_i32_e32 v109, 31, v108
	s_addc_u32 s7, s41, 0
	v_and_or_b32 v102, v101, s3, v102
	v_ashrrev_i32_e32 v111, 6, v108
	v_ashrrev_i32_e32 v101, 4, v108
	v_and_b32_e32 v104, 0x78, v103
	v_lshl_add_u64 v[106:107], v[108:109], 4, s[40:41]
	s_mov_b64 s[4:5], 0x20a00000
	v_and_b32_e32 v108, 63, v108
	v_lshl_add_u64 v[106:107], v[106:107], 0, s[4:5]
	v_lshlrev_b32_e32 v103, 9, v101
	v_lshlrev_b32_e32 v109, 2, v104
	v_add_u32_e32 v124, 0, v110
	s_add_u32 s4, s0, 0x60
	v_lshl_add_u32 v108, v108, 4, 0
	v_mov_b32_e32 v105, 0
	s_mov_b32 s11, 0
	v_add3_u32 v103, 0, v103, v109
	s_movk_i32 s3, 0x4000
	v_add_u32_e32 v125, 0x4000, v124
	v_lshl_add_u32 v126, v111, 11, 0
; #define LAS __attribute__((address_space(3)))
; __device__ void p_weights_prod(const Args& a, LAS unsigned char* lds) {
;     ...
;         {
;             const int rr = tid >> 4, c8 = (tid & 15) * 8;
;             const float* src = a.w_in + (size_t)l * DM * INW + (size_t)(kblk * 32 + rr) * INW + 1280 + g * 128 + c8;
;             const f32x4* msrc = (const f32x4*)(MM + (size_t)(l * 4 + g) * 128 * 256) + tid;
;             f32x4 mreg[16];
; #pragma unroll
;             for (int j = 0; j < 16; ++j) mreg[j] = msrc[j * NTHREADS];
;             *(LAS f32x4*)(wt + rr * 128 + c8) = *(const f32x4*)src; *(LAS f32x4*)(wt + rr * 128 + c8 + 4) = *(const f32x4*)(src + 4);
; #pragma unroll
;             for (int j = 0; j < 16; ++j) ((LAS f32x4*)mmt)[tid + j * NTHREADS] = mreg[j];
;         }
;         __syncthreads();
;         f32x4 acc[4];
; #pragma unroll
;         for (int r2 = 0; r2 < 4; ++r2) acc[r2] = (f32x4){0.f, 0.f, 0.f, 0.f};
	v_lshlrev_b32_e32 v127, 2, v111
	s_addc_u32 s5, s1, 0
	s_mov_b32 s14, 0x14000
	v_add_u32_e32 v128, 0x14000, v124
	s_mov_b32 s15, 0x16000
	v_add_u32_e32 v129, 0x16000, v124
	s_mov_b32 s33, 0x18000
	v_add_u32_e32 v130, 0x18000, v124
	s_mov_b32 s34, 0x1a000
	v_add_u32_e32 v131, 0x1a000, v124
	s_mov_b32 s35, 0x1c000
	v_add_u32_e32 v132, 0x1c000, v124
	s_mov_b32 s36, 0x1e000
	v_add_u32_e32 v133, 0x1e000, v124
	v_add_u32_e32 v134, 0x20000, v124
	v_add_u32_e32 v135, 0x22000, v124
	v_add_u32_e32 v136, 0x4000, v108
	s_movk_i32 s37, 0x2400
	s_movk_i32 s44, 0x2000
	s_movk_i32 s45, 0x6000
	s_mov_b32 s46, 0x8000
	s_mov_b32 s47, 0xa000
	s_mov_b32 s48, 0xc000
	s_mov_b32 s49, 0xe000
	s_mov_b32 s50, 0x10000
	s_mov_b32 s51, 0x12000
	v_lshlrev_b32_e32 v104, 2, v104
	s_mov_b64 s[12:13], 0x1400
	s_movk_i32 s52, 0x1000
	s_mov_b32 s53, s2
	s_ashr_i32 s55, s53, 7
	s_bfe_u32 s54, s53, 0x20005
	s_mul_i32 s56, s55, 0x900000
	s_mul_hi_i32 s10, s55, 0x900000
	s_add_u32 s58, s22, s56
	s_addc_u32 s59, s23, s10
	s_lshl_b32 s10, s53, 5
	s_and_b32 s56, s10, 0x3e0
	v_add_u32_e32 v110, s56, v101
	v_mov_b64_e32 v[108:109], s[58:59]
	v_mad_i64_i32 v[108:109], s[58:59], v110, s37, v[108:109]
	s_lshl_b32 s10, s54, 9
	v_lshl_add_u64 v[108:109], v[108:109], 0, s[10:11]
	s_lshl_b32 s10, s55, 2
	s_or_b32 s58, s10, s54
	v_lshl_add_u64 v[108:109], v[108:109], 0, v[104:105]
	s_ashr_i32 s59, s58, 31
	v_add_co_u32_e32 v110, vcc, s52, v108
	s_lshl_b64 s[58:59], s[58:59], 17
	s_nop 0
	v_addc_co_u32_e32 v111, vcc, 0, v109, vcc
	v_lshl_add_u64 v[186:187], v[106:107], 0, s[58:59]
	v_add_co_u32_e32 v120, vcc, s44, v186
	v_lshl_add_u64 v[112:113], v[108:109], 0, s[12:13]
	s_nop 0
	v_addc_co_u32_e32 v121, vcc, 0, v187, vcc
	v_add_co_u32_e32 v138, vcc, s3, v186
	s_waitcnt lgkmcnt(0)
	s_nop 0
	v_addc_co_u32_e32 v139, vcc, 0, v187, vcc
	v_add_co_u32_e32 v142, vcc, s45, v186
	s_nop 0
	v_addc_co_u32_e32 v143, vcc, 0, v187, vcc
	v_add_co_u32_e32 v146, vcc, s46, v186
	s_nop 1
	v_addc_co_u32_e32 v147, vcc, 0, v187, vcc
	v_add_co_u32_e32 v150, vcc, s47, v186
	global_load_dwordx4 v[108:111], v[110:111], off offset:1024
	s_nop 0
	global_load_dwordx4 v[112:115], v[112:113], off offset:16
	v_addc_co_u32_e32 v151, vcc, 0, v187, vcc
	v_add_co_u32_e32 v154, vcc, s48, v186
	global_load_dwordx4 v[116:119], v[186:187], off
	s_nop 0
	global_load_dwordx4 v[120:123], v[120:121], off
	v_addc_co_u32_e32 v155, vcc, 0, v187, vcc
	v_add_co_u32_e32 v158, vcc, s49, v186
	global_load_dwordx4 v[138:141], v[138:139], off
	s_nop 0
	global_load_dwordx4 v[142:145], v[142:143], off
	v_addc_co_u32_e32 v159, vcc, 0, v187, vcc
	v_add_co_u32_e32 v162, vcc, s50, v186
	global_load_dwordx4 v[146:149], v[146:147], off
	s_nop 0
	global_load_dwordx4 v[150:153], v[150:151], off
	v_addc_co_u32_e32 v163, vcc, 0, v187, vcc
	v_add_co_u32_e32 v166, vcc, s51, v186
	s_mov_b32 s10, -4
	s_nop 0
	v_addc_co_u32_e32 v167, vcc, 0, v187, vcc
	v_add_co_u32_e32 v170, vcc, s14, v186
	v_mov_b32_e32 v137, v126
	s_nop 0
	v_addc_co_u32_e32 v171, vcc, 0, v187, vcc
	v_add_co_u32_e32 v174, vcc, s15, v186
	s_nop 1
	v_addc_co_u32_e32 v175, vcc, 0, v187, vcc
	v_add_co_u32_e32 v178, vcc, s33, v186
	global_load_dwordx4 v[154:157], v[154:155], off
	s_nop 0
	global_load_dwordx4 v[158:161], v[158:159], off
	s_nop 0
	global_load_dwordx4 v[162:165], v[162:163], off
	s_nop 0
	global_load_dwordx4 v[166:169], v[166:167], off
	s_nop 0
	global_load_dwordx4 v[170:173], v[170:171], off
	s_nop 0
	global_load_dwordx4 v[174:177], v[174:175], off
	v_addc_co_u32_e32 v179, vcc, 0, v187, vcc
	v_add_co_u32_e32 v182, vcc, s34, v186
	s_nop 1
	v_addc_co_u32_e32 v183, vcc, 0, v187, vcc
	v_add_co_u32_e32 v188, vcc, s35, v186
	global_load_dwordx4 v[178:181], v[178:179], off
	s_nop 0
	global_load_dwordx4 v[182:185], v[182:183], off
	v_addc_co_u32_e32 v189, vcc, 0, v187, vcc
	v_add_co_u32_e32 v190, vcc, s36, v186
	s_nop 1
	v_addc_co_u32_e32 v191, vcc, 0, v187, vcc
	global_load_dwordx4 v[186:189], v[188:189], off
	s_nop 0
	global_load_dwordx4 v[190:193], v[190:191], off
	s_waitcnt vmcnt(0)
	ds_write_b128 v3, v[8:11]
	ds_write_b128 v3, v[12:15] offset:16
	ds_write_b128 v24, v[16:19] offset:16384
	ds_write_b128 v24, v[20:23] offset:24576
	ds_write_b128 v24, v[38:41] offset:32768
	ds_write_b128 v24, v[42:45] offset:40960
	ds_write_b128 v24, v[46:49] offset:49152
	ds_write_b128 v24, v[50:53] offset:57344
	ds_write_b128 v25, v[54:57] offset:49152
	ds_write_b128 v25, v[58:61] offset:57344
	ds_write_b128 v28, v[62:65]
	ds_write_b128 v29, v[66:69]
	ds_write_b128 v30, v[70:73]
	ds_write_b128 v31, v[74:77]
	ds_write_b128 v32, v[78:81]
	ds_write_b128 v33, v[82:85]
	ds_write_b128 v34, v[86:89]
	ds_write_b128 v35, v[90:93]
	v_mov_b32_e32 v38, v36
	v_mov_b32_e32 v10, 0
	v_mov_b32_e32 v11, v5
	v_mov_b32_e32 v8, 0
	v_mov_b32_e32 v9, v5
	v_mov_b32_e32 v22, 0
	v_mov_b32_e32 v23, v5
	v_mov_b32_e32 v20, 0
	v_mov_b32_e32 v21, v5
	v_mov_b32_e32 v14, 0
	v_mov_b32_e32 v15, v5
	v_mov_b32_e32 v12, 0
	v_mov_b32_e32 v13, v5
	v_mov_b32_e32 v18, 0
	v_mov_b32_e32 v19, v5
	v_mov_b32_e32 v16, 0
	v_mov_b32_e32 v17, v5
	s_waitcnt vmcnt(0)
	ds_write_b128 v103, v[108:111]
	ds_write_b128 v103, v[112:115] offset:16
	ds_write_b128 v124, v[116:119] offset:16384
	ds_write_b128 v124, v[120:123] offset:24576
	ds_write_b128 v124, v[138:141] offset:32768
	ds_write_b128 v124, v[142:145] offset:40960
	ds_write_b128 v124, v[146:149] offset:49152
	ds_write_b128 v124, v[150:153] offset:57344
	ds_write_b128 v125, v[154:157] offset:49152
	ds_write_b128 v125, v[158:161] offset:57344
	ds_write_b128 v128, v[162:165]
	ds_write_b128 v129, v[166:169]
	ds_write_b128 v130, v[170:173]
	ds_write_b128 v131, v[174:177]
	ds_write_b128 v132, v[178:181]
	ds_write_b128 v133, v[182:185]
	ds_write_b128 v134, v[186:189]
	ds_write_b128 v135, v[190:193]
	v_mov_b32_e32 v138, v136
	v_mov_b32_e32 v110, 0
	v_mov_b32_e32 v111, v105
	v_mov_b32_e32 v108, 0
	v_mov_b32_e32 v109, v105
	v_mov_b32_e32 v122, 0
	v_mov_b32_e32 v123, v105
	v_mov_b32_e32 v120, 0
	v_mov_b32_e32 v121, v105
	v_mov_b32_e32 v114, 0
	v_mov_b32_e32 v115, v105
	v_mov_b32_e32 v112, 0
	v_mov_b32_e32 v113, v105
	v_mov_b32_e32 v118, 0
	v_mov_b32_e32 v119, v105
	v_mov_b32_e32 v116, 0
	v_mov_b32_e32 v117, v105
	s_waitcnt lgkmcnt(0)
	s_barrier
; #define LAS __attribute__((address_space(3)))
; __device__ void p_weights_prod(const Args& a, LAS unsigned char* lds) {
;     ...
;     LAS float* wt = (LAS float*)lds;
;     LAS float* mmt = (LAS float*)(lds + 16384);
;     for (int u = blockIdx.x; u < 256; u += gridDim.x) {
;         const int l = u >> 7, g = (u >> 5) & 3, kblk = u & 31, pn = 7 + g;
;         __syncthreads();
;         {
;             const int rr = tid >> 4, c8 = (tid & 15) * 8;
;             const float* src = a.w_in + (size_t)l * DM * INW + (size_t)(kblk * 32 + rr) * INW + 1280 + g * 128 + c8;
;             const f32x4* msrc = (const f32x4*)(MM + (size_t)(l * 4 + g) * 128 * 256) + tid;
;             f32x4 mreg[16];
; #pragma unroll
;             for (int j = 0; j < 16; ++j) mreg[j] = msrc[j * NTHREADS];
;             *(LAS f32x4*)(wt + rr * 128 + c8) = *(const f32x4*)src; *(LAS f32x4*)(wt + rr * 128 + c8 + 4) = *(const f32x4*)(src + 4);
; #pragma unroll
;             for (int j = 0; j < 16; ++j) ((LAS f32x4*)mmt)[tid + j * NTHREADS] = mreg[j];
;         }
;         __syncthreads();
;         f32x4 acc[4];
; #pragma unroll
;         for (int r2 = 0; r2 < 4; ++r2) acc[r2] = (f32x4){0.f, 0.f, 0.f, 0.f};
	v_mov_b32_e32 v8, v0
	v_lshlrev_b32_e32 v10, 4, v8
	s_load_dword s9, s[0:1], 0x60
	s_add_u32 s6, s40, 0x1fb00000
	v_lshlrev_b32_e32 v1, 1, v8
	v_and_b32_e32 v2, 0x90, v10
	s_movk_i32 s3, 0x6c
	v_lshlrev_b32_e32 v3, 3, v8
	v_ashrrev_i32_e32 v9, 31, v8
	s_addc_u32 s7, s41, 0
	v_and_or_b32 v2, v1, s3, v2
	v_ashrrev_i32_e32 v11, 6, v8
	v_ashrrev_i32_e32 v1, 4, v8
	v_and_b32_e32 v4, 0x78, v3
	v_lshl_add_u64 v[6:7], v[8:9], 4, s[40:41]
	s_mov_b64 s[4:5], 0x20a00000
	v_and_b32_e32 v8, 63, v8
	v_lshl_add_u64 v[6:7], v[6:7], 0, s[4:5]
	v_lshlrev_b32_e32 v3, 9, v1
	v_lshlrev_b32_e32 v9, 2, v4
	v_add_u32_e32 v24, 0, v10
	s_add_u32 s4, s0, 0x60
	v_lshl_add_u32 v8, v8, 4, 0
	v_mov_b32_e32 v5, 0
	s_mov_b32 s11, 0
	v_add3_u32 v3, 0, v3, v9
	s_movk_i32 s3, 0x4000
	v_add_u32_e32 v25, 0x4000, v24
	v_lshl_add_u32 v26, v11, 11, 0
	v_lshlrev_b32_e32 v27, 2, v11
	s_addc_u32 s5, s1, 0
	s_mov_b32 s14, 0x14000
	v_add_u32_e32 v28, 0x14000, v24
	s_mov_b32 s15, 0x16000
	v_add_u32_e32 v29, 0x16000, v24
	s_mov_b32 s33, 0x18000
	v_add_u32_e32 v30, 0x18000, v24
	s_mov_b32 s34, 0x1a000
	v_add_u32_e32 v31, 0x1a000, v24
	s_mov_b32 s35, 0x1c000
	v_add_u32_e32 v32, 0x1c000, v24
	s_mov_b32 s36, 0x1e000
	v_add_u32_e32 v33, 0x1e000, v24
	v_add_u32_e32 v34, 0x20000, v24
	v_add_u32_e32 v35, 0x22000, v24
	v_add_u32_e32 v36, 0x4000, v8
	s_movk_i32 s37, 0x2400
	s_movk_i32 s44, 0x2000
	s_movk_i32 s45, 0x6000
	s_mov_b32 s46, 0x8000
	s_mov_b32 s47, 0xa000
	s_mov_b32 s48, 0xc000
	s_mov_b32 s49, 0xe000
	s_mov_b32 s50, 0x10000
	s_mov_b32 s51, 0x12000
	v_lshlrev_b32_e32 v4, 2, v4
	s_mov_b64 s[12:13], 0x1400
	s_movk_i32 s52, 0x1000
	s_mov_b32 s53, s2
	s_ashr_i32 s55, s53, 7
	s_bfe_u32 s54, s53, 0x20005
	s_mul_i32 s56, s55, 0x900000
	s_mul_hi_i32 s10, s55, 0x900000
	s_add_u32 s58, s22, s56
	s_addc_u32 s59, s23, s10
	s_lshl_b32 s10, s53, 5
	s_and_b32 s56, s10, 0x3e0
	v_add_u32_e32 v10, s56, v1
	v_mov_b64_e32 v[8:9], s[58:59]
	v_mad_i64_i32 v[8:9], s[58:59], v10, s37, v[8:9]
	s_lshl_b32 s10, s54, 9
	v_lshl_add_u64 v[8:9], v[8:9], 0, s[10:11]
	s_lshl_b32 s10, s55, 2
	s_or_b32 s58, s10, s54
	v_lshl_add_u64 v[8:9], v[8:9], 0, v[4:5]
	s_ashr_i32 s59, s58, 31
	v_add_co_u32_e32 v10, vcc, s52, v8
	s_lshl_b64 s[58:59], s[58:59], 17
	s_nop 0
	v_addc_co_u32_e32 v11, vcc, 0, v9, vcc
	v_lshl_add_u64 v[86:87], v[6:7], 0, s[58:59]
	v_add_co_u32_e32 v20, vcc, s44, v86
	v_lshl_add_u64 v[12:13], v[8:9], 0, s[12:13]
	s_nop 0
	v_addc_co_u32_e32 v21, vcc, 0, v87, vcc
	v_add_co_u32_e32 v38, vcc, s3, v86
	s_waitcnt lgkmcnt(0)
	s_nop 0
	v_addc_co_u32_e32 v39, vcc, 0, v87, vcc
	v_add_co_u32_e32 v42, vcc, s45, v86
	s_nop 0
	v_addc_co_u32_e32 v43, vcc, 0, v87, vcc
	v_add_co_u32_e32 v46, vcc, s46, v86
	s_nop 1
	v_addc_co_u32_e32 v47, vcc, 0, v87, vcc
	v_add_co_u32_e32 v50, vcc, s47, v86
	s_nop 0
	v_addc_co_u32_e32 v51, vcc, 0, v87, vcc
	v_add_co_u32_e32 v54, vcc, s48, v86
	s_nop 0
	v_addc_co_u32_e32 v55, vcc, 0, v87, vcc
	v_add_co_u32_e32 v58, vcc, s49, v86
	s_nop 0
	v_addc_co_u32_e32 v59, vcc, 0, v87, vcc
	v_add_co_u32_e32 v62, vcc, s50, v86
	s_nop 0
	v_addc_co_u32_e32 v63, vcc, 0, v87, vcc
	v_add_co_u32_e32 v66, vcc, s51, v86
	s_mov_b32 s10, -4
	s_nop 0
	v_addc_co_u32_e32 v67, vcc, 0, v87, vcc
	v_add_co_u32_e32 v70, vcc, s14, v86
	v_mov_b32_e32 v37, v26
	s_nop 0
	v_addc_co_u32_e32 v71, vcc, 0, v87, vcc
	v_add_co_u32_e32 v74, vcc, s15, v86
	s_nop 1
	v_addc_co_u32_e32 v75, vcc, 0, v87, vcc
	v_add_co_u32_e32 v78, vcc, s33, v86
	s_nop 0
	s_nop 0
	s_nop 0
	s_nop 0
	s_nop 0
	v_addc_co_u32_e32 v79, vcc, 0, v87, vcc
	v_add_co_u32_e32 v82, vcc, s34, v86
	s_nop 1
	v_addc_co_u32_e32 v83, vcc, 0, v87, vcc
	v_add_co_u32_e32 v88, vcc, s35, v86
	s_nop 0
	v_addc_co_u32_e32 v89, vcc, 0, v87, vcc
	v_add_co_u32_e32 v90, vcc, s36, v86
	s_nop 1
	v_addc_co_u32_e32 v91, vcc, 0, v87, vcc
	s_nop 0
	s_waitcnt vmcnt(0)
	v_mov_b32_e32 v38, v36
	v_mov_b32_e32 v10, 0
	v_mov_b32_e32 v11, v5
	v_mov_b32_e32 v8, 0
	v_mov_b32_e32 v9, v5
	v_mov_b32_e32 v22, 0
	v_mov_b32_e32 v23, v5
	v_mov_b32_e32 v20, 0
	v_mov_b32_e32 v21, v5
	v_mov_b32_e32 v14, 0
	v_mov_b32_e32 v15, v5
	v_mov_b32_e32 v12, 0
	v_mov_b32_e32 v13, v5
	v_mov_b32_e32 v18, 0
	v_mov_b32_e32 v19, v5
	v_mov_b32_e32 v16, 0
	v_mov_b32_e32 v17, v5
